# lambda vectors of the forward LRU direction loaded up front (3 serialized waits removed)
# speedup vs baseline: 1.0356x; 1.0032x over previous
; __device__ __forceinline__ float bf2f(bf16_t b) { return __uint_as_float(((unsigned)b) << 16); }
; __device__ __forceinline__ bf16_t f2bf(float f) { unsigned u = __float_as_uint(f); return (bf16_t)((u + 0x7fffu + ((u >> 16) & 1u)) >> 16); }
; template <int MODE> __device__ void mixer_lru(const Params& p, int l, int n, LAS unsigned char* lds) {
;     ...
;             const int ch = tid;
;             const float cw0 = p.in[4][(size_t)(l * 4 + 0) * 512 + ch], cw1 = p.in[4][(size_t)(l * 4 + 1) * 512 + ch], cw2 = p.in[4][(size_t)(l * 4 + 2) * 512 + ch], cw3 = p.in[4][(size_t)(l * 4 + 3) * 512 + ch];
;             const float cb = p.in[5][(size_t)l * 512 + ch];
;             bf16_t xs[67];
; #pragma unroll
;             for (int i = 0; i < 67; ++i) { const int s_ = t0 - 2 + i; const int sc = s_ < 0 ? 0 : (s_ >= S ? S - 1 : s_); const bf16_t v = proj[(size_t)sc * DINP + ch]; xs[i] = s_ == sc ? v : (bf16_t)0; }
; #pragma unroll
;             for (int t = 0; t < 64; ++t) { const float xc = cb + cw0 * bf2f(xs[t]) + cw1 * bf2f(xs[t + 1]) + cw2 * bf2f(xs[t + 2]) + cw3 * bf2f(xs[t + 3]); XC[t * 520 + ch] = f2bf(xc); }
.LBB0_192:
	v_mov_b32_e32 v100, v245
	s_lshl_b32 s28, s4, 6
	v_readlane_b32 s0, v253, 16
	v_readlane_b32 s1, v253, 17
	v_readlane_b32 s88, v255, 22
	v_readlane_b32 s89, v255, 23
	v_readfirstlane_b32 s29, v100
	v_and_b32_e32 v0, 0xff, v100
	v_lshlrev_b32_e32 v1, 3, v0
	v_lshlrev_b32_e32 v0, 2, v0
	s_nop 4
	s_lshr_b32 s29, s29, 8
	global_load_dwordx2 v[2:3], v1, s[14:15]
	global_load_dwordx2 v[4:5], v1, s[88:89]
	global_load_dwordx2 v[6:7], v1, s[8:9]
	global_load_dwordx2 v[8:9], v1, s[10:11]
	global_load_dwordx2 v[10:11], v1, s[12:13]
	s_lshl_b32 s30, s29, 5
	s_add_i32 s30, s30, s28
	s_add_i32 s30, s30, -2
	s_max_i32 s31, s30, 0
	s_cmp_eq_u32 s31, s30
	s_cselect_b32 s92, -1, 0
	s_mul_i32 s31, s31, 0x1600
	s_add_u32 s90, s0, s31
	s_addc_u32 s91, s1, 0
	global_load_dword v12, v0, s[90:91]
	s_add_i32 s34, s30, 1
	s_max_i32 s31, s34, 0
	s_cmp_eq_u32 s31, s34
	s_cselect_b32 s93, -1, 0
	s_mul_i32 s31, s31, 0x1600
	s_add_u32 s90, s0, s31
	s_addc_u32 s91, s1, 0
	global_load_dword v13, v0, s[90:91]
	s_add_i32 s31, s30, 2
	s_mul_i32 s31, s31, 0x1600
	s_add_u32 s90, s0, s31
	s_addc_u32 s91, s1, 0
	global_load_dword v14, v0, s[90:91]
	s_add_u32 s90, s90, 0x1600
	s_addc_u32 s91, s91, 0
	global_load_dword v15, v0, s[90:91]
	s_add_u32 s90, s90, 0x1600
	s_addc_u32 s91, s91, 0
	global_load_dword v16, v0, s[90:91]
	s_add_u32 s90, s90, 0x1600
	s_addc_u32 s91, s91, 0
	global_load_dword v17, v0, s[90:91]
	s_add_u32 s90, s90, 0x1600
	s_addc_u32 s91, s91, 0
	global_load_dword v18, v0, s[90:91]
	s_add_u32 s90, s90, 0x1600
	s_addc_u32 s91, s91, 0
	global_load_dword v19, v0, s[90:91]
	s_add_u32 s90, s90, 0x1600
	s_addc_u32 s91, s91, 0
	global_load_dword v20, v0, s[90:91]
	s_add_u32 s90, s90, 0x1600
	s_addc_u32 s91, s91, 0
	global_load_dword v21, v0, s[90:91]
	s_add_u32 s90, s90, 0x1600
	s_addc_u32 s91, s91, 0
	global_load_dword v22, v0, s[90:91]
	s_add_u32 s90, s90, 0x1600
	s_addc_u32 s91, s91, 0
	global_load_dword v23, v0, s[90:91]
	s_add_u32 s90, s90, 0x1600
	s_addc_u32 s91, s91, 0
	global_load_dword v24, v0, s[90:91]
	s_add_u32 s90, s90, 0x1600
	s_addc_u32 s91, s91, 0
	global_load_dword v25, v0, s[90:91]
	s_add_u32 s90, s90, 0x1600
	s_addc_u32 s91, s91, 0
	global_load_dword v26, v0, s[90:91]
	s_add_u32 s90, s90, 0x1600
	s_addc_u32 s91, s91, 0
	global_load_dword v27, v0, s[90:91]
	s_add_u32 s90, s90, 0x1600
	s_addc_u32 s91, s91, 0
	global_load_dword v28, v0, s[90:91]
	s_add_u32 s90, s90, 0x1600
	s_addc_u32 s91, s91, 0
	global_load_dword v29, v0, s[90:91]
	s_add_u32 s90, s90, 0x1600
	s_addc_u32 s91, s91, 0
	global_load_dword v30, v0, s[90:91]
	s_add_u32 s90, s90, 0x1600
	s_addc_u32 s91, s91, 0
	global_load_dword v31, v0, s[90:91]
	s_add_u32 s90, s90, 0x1600
	s_addc_u32 s91, s91, 0
	global_load_dword v32, v0, s[90:91]
	s_add_u32 s90, s90, 0x1600
	s_addc_u32 s91, s91, 0
	global_load_dword v33, v0, s[90:91]
	s_add_u32 s90, s90, 0x1600
	s_addc_u32 s91, s91, 0
	global_load_dword v34, v0, s[90:91]
	s_add_u32 s90, s90, 0x1600
	s_addc_u32 s91, s91, 0
	global_load_dword v35, v0, s[90:91]
	s_add_u32 s90, s90, 0x1600
	s_addc_u32 s91, s91, 0
	global_load_dword v36, v0, s[90:91]
	s_add_u32 s90, s90, 0x1600
	s_addc_u32 s91, s91, 0
	global_load_dword v37, v0, s[90:91]
	s_add_u32 s90, s90, 0x1600
	s_addc_u32 s91, s91, 0
	global_load_dword v38, v0, s[90:91]
	s_add_u32 s90, s90, 0x1600
	s_addc_u32 s91, s91, 0
	global_load_dword v39, v0, s[90:91]
	s_add_u32 s90, s90, 0x1600
	s_addc_u32 s91, s91, 0
	global_load_dword v40, v0, s[90:91]
	s_add_u32 s90, s90, 0x1600
	s_addc_u32 s91, s91, 0
	global_load_dword v41, v0, s[90:91]
	s_add_u32 s90, s90, 0x1600
	s_addc_u32 s91, s91, 0
	global_load_dword v42, v0, s[90:91]
	s_add_u32 s90, s90, 0x1600
	s_addc_u32 s91, s91, 0
	global_load_dword v43, v0, s[90:91]
	s_add_u32 s90, s90, 0x1600
	s_addc_u32 s91, s91, 0
	global_load_dword v44, v0, s[90:91]
	s_add_u32 s90, s90, 0x1600
	s_addc_u32 s91, s91, 0
	global_load_dword v45, v0, s[90:91]
	s_add_i32 s34, s30, 34
	s_min_i32 s31, s34, 0x3fff
	s_cmp_eq_u32 s31, s34
	s_cselect_b32 s94, -1, 0
	s_mul_i32 s31, s31, 0x1600
	s_add_u32 s90, s0, s31
	s_addc_u32 s91, s1, 0
	global_load_dword v46, v0, s[90:91]
	s_mul_i32 s95, s29, 0x8200
	v_add_u32_e32 v92, s95, v0
	s_waitcnt vmcnt(31)
	v_and_b32_e32 v12, s92, v12
	v_lshlrev_b32_e32 v48, 16, v12
	v_and_b32_e32 v12, 0xffff0000, v12
	v_and_b32_e32 v13, s93, v13
	v_lshlrev_b32_e32 v49, 16, v13
	v_and_b32_e32 v13, 0xffff0000, v13
	v_lshlrev_b32_e32 v50, 16, v14
	v_and_b32_e32 v14, 0xffff0000, v14
	v_lshlrev_b32_e32 v51, 16, v15
	v_and_b32_e32 v15, 0xffff0000, v15
	v_fma_f32 v84, v4, v48, v2
	v_fma_f32 v85, v5, v12, v3
	v_fmac_f32_e32 v84, v6, v49
	v_fmac_f32_e32 v85, v7, v13
	v_fmac_f32_e32 v84, v8, v50
	v_fmac_f32_e32 v85, v9, v14
	v_fmac_f32_e32 v84, v10, v51
	v_fmac_f32_e32 v85, v11, v15
	v_cvt_pk_bf16_f32 v84, v84, v85
	ds_write_b32 v92, v84
	s_waitcnt vmcnt(30)
	v_lshlrev_b32_e32 v52, 16, v16
	v_and_b32_e32 v16, 0xffff0000, v16
	v_fma_f32 v86, v4, v49, v2
	v_fma_f32 v87, v5, v13, v3
	v_fmac_f32_e32 v86, v6, v50
	v_fmac_f32_e32 v87, v7, v14
	v_fmac_f32_e32 v86, v8, v51
	v_fmac_f32_e32 v87, v9, v15
	v_fmac_f32_e32 v86, v10, v52
	v_fmac_f32_e32 v87, v11, v16
	v_cvt_pk_bf16_f32 v86, v86, v87
	ds_write_b32 v92, v86 offset:1040
	s_waitcnt vmcnt(29)
	v_lshlrev_b32_e32 v53, 16, v17
	v_and_b32_e32 v17, 0xffff0000, v17
	v_fma_f32 v84, v4, v50, v2
	v_fma_f32 v85, v5, v14, v3
	v_fmac_f32_e32 v84, v6, v51
	v_fmac_f32_e32 v85, v7, v15
	v_fmac_f32_e32 v84, v8, v52
	v_fmac_f32_e32 v85, v9, v16
	v_fmac_f32_e32 v84, v10, v53
	v_fmac_f32_e32 v85, v11, v17
	v_cvt_pk_bf16_f32 v84, v84, v85
	ds_write_b32 v92, v84 offset:2080
	s_waitcnt vmcnt(28)
; __device__ __forceinline__ float bf2f(bf16_t b) { return __uint_as_float(((unsigned)b) << 16); }
; __device__ __forceinline__ bf16_t f2bf(float f) { unsigned u = __float_as_uint(f); return (bf16_t)((u + 0x7fffu + ((u >> 16) & 1u)) >> 16); }
; template <int MODE> __device__ void mixer_lru(const Params& p, int l, int n, LAS unsigned char* lds) {
;     ...
;             for (int i = 0; i < 67; ++i) { const int s_ = t0 - 2 + i; const int sc = s_ < 0 ? 0 : (s_ >= S ? S - 1 : s_); const bf16_t v = proj[(size_t)sc * DINP + ch]; xs[i] = s_ == sc ? v : (bf16_t)0; }
; #pragma unroll
;             for (int t = 0; t < 64; ++t) { const float xc = cb + cw0 * bf2f(xs[t]) + cw1 * bf2f(xs[t + 1]) + cw2 * bf2f(xs[t + 2]) + cw3 * bf2f(xs[t + 3]); XC[t * 520 + ch] = f2bf(xc); }
	v_lshlrev_b32_e32 v54, 16, v18
	v_and_b32_e32 v18, 0xffff0000, v18
	v_fma_f32 v86, v4, v51, v2
	v_fma_f32 v87, v5, v15, v3
	v_fmac_f32_e32 v86, v6, v52
	v_fmac_f32_e32 v87, v7, v16
	v_fmac_f32_e32 v86, v8, v53
	v_fmac_f32_e32 v87, v9, v17
	v_fmac_f32_e32 v86, v10, v54
	v_fmac_f32_e32 v87, v11, v18
	v_cvt_pk_bf16_f32 v86, v86, v87
	ds_write_b32 v92, v86 offset:3120
	s_waitcnt vmcnt(27)
	v_lshlrev_b32_e32 v55, 16, v19
	v_and_b32_e32 v19, 0xffff0000, v19
	v_fma_f32 v84, v4, v52, v2
	v_fma_f32 v85, v5, v16, v3
	v_fmac_f32_e32 v84, v6, v53
	v_fmac_f32_e32 v85, v7, v17
	v_fmac_f32_e32 v84, v8, v54
	v_fmac_f32_e32 v85, v9, v18
	v_fmac_f32_e32 v84, v10, v55
	v_fmac_f32_e32 v85, v11, v19
	v_cvt_pk_bf16_f32 v84, v84, v85
	ds_write_b32 v92, v84 offset:4160
	s_waitcnt vmcnt(26)
	v_lshlrev_b32_e32 v56, 16, v20
	v_and_b32_e32 v20, 0xffff0000, v20
	v_fma_f32 v86, v4, v53, v2
	v_fma_f32 v87, v5, v17, v3
	v_fmac_f32_e32 v86, v6, v54
	v_fmac_f32_e32 v87, v7, v18
	v_fmac_f32_e32 v86, v8, v55
	v_fmac_f32_e32 v87, v9, v19
	v_fmac_f32_e32 v86, v10, v56
	v_fmac_f32_e32 v87, v11, v20
	v_cvt_pk_bf16_f32 v86, v86, v87
	ds_write_b32 v92, v86 offset:5200
	s_waitcnt vmcnt(25)
	v_lshlrev_b32_e32 v57, 16, v21
	v_and_b32_e32 v21, 0xffff0000, v21
	v_fma_f32 v84, v4, v54, v2
	v_fma_f32 v85, v5, v18, v3
	v_fmac_f32_e32 v84, v6, v55
	v_fmac_f32_e32 v85, v7, v19
	v_fmac_f32_e32 v84, v8, v56
	v_fmac_f32_e32 v85, v9, v20
	v_fmac_f32_e32 v84, v10, v57
	v_fmac_f32_e32 v85, v11, v21
	v_cvt_pk_bf16_f32 v84, v84, v85
	ds_write_b32 v92, v84 offset:6240
	s_waitcnt vmcnt(24)
	v_lshlrev_b32_e32 v58, 16, v22
	v_and_b32_e32 v22, 0xffff0000, v22
	v_fma_f32 v86, v4, v55, v2
	v_fma_f32 v87, v5, v19, v3
	v_fmac_f32_e32 v86, v6, v56
	v_fmac_f32_e32 v87, v7, v20
	v_fmac_f32_e32 v86, v8, v57
	v_fmac_f32_e32 v87, v9, v21
	v_fmac_f32_e32 v86, v10, v58
	v_fmac_f32_e32 v87, v11, v22
	v_cvt_pk_bf16_f32 v86, v86, v87
	ds_write_b32 v92, v86 offset:7280
	s_waitcnt vmcnt(23)
	v_lshlrev_b32_e32 v59, 16, v23
	v_and_b32_e32 v23, 0xffff0000, v23
	v_fma_f32 v84, v4, v56, v2
	v_fma_f32 v85, v5, v20, v3
	v_fmac_f32_e32 v84, v6, v57
	v_fmac_f32_e32 v85, v7, v21
	v_fmac_f32_e32 v84, v8, v58
	v_fmac_f32_e32 v85, v9, v22
	v_fmac_f32_e32 v84, v10, v59
	v_fmac_f32_e32 v85, v11, v23
	v_cvt_pk_bf16_f32 v84, v84, v85
	ds_write_b32 v92, v84 offset:8320
	s_waitcnt vmcnt(22)
	v_lshlrev_b32_e32 v60, 16, v24
	v_and_b32_e32 v24, 0xffff0000, v24
	v_fma_f32 v86, v4, v57, v2
	v_fma_f32 v87, v5, v21, v3
	v_fmac_f32_e32 v86, v6, v58
	v_fmac_f32_e32 v87, v7, v22
	v_fmac_f32_e32 v86, v8, v59
	v_fmac_f32_e32 v87, v9, v23
	v_fmac_f32_e32 v86, v10, v60
	v_fmac_f32_e32 v87, v11, v24
	v_cvt_pk_bf16_f32 v86, v86, v87
	ds_write_b32 v92, v86 offset:9360
	s_waitcnt vmcnt(21)
	v_lshlrev_b32_e32 v61, 16, v25
	v_and_b32_e32 v25, 0xffff0000, v25
	v_fma_f32 v84, v4, v58, v2
	v_fma_f32 v85, v5, v22, v3
	v_fmac_f32_e32 v84, v6, v59
	v_fmac_f32_e32 v85, v7, v23
	v_fmac_f32_e32 v84, v8, v60
	v_fmac_f32_e32 v85, v9, v24
	v_fmac_f32_e32 v84, v10, v61
	v_fmac_f32_e32 v85, v11, v25
	v_cvt_pk_bf16_f32 v84, v84, v85
	ds_write_b32 v92, v84 offset:10400
	s_waitcnt vmcnt(20)
	v_lshlrev_b32_e32 v62, 16, v26
	v_and_b32_e32 v26, 0xffff0000, v26
	v_fma_f32 v86, v4, v59, v2
	v_fma_f32 v87, v5, v23, v3
	v_fmac_f32_e32 v86, v6, v60
	v_fmac_f32_e32 v87, v7, v24
	v_fmac_f32_e32 v86, v8, v61
	v_fmac_f32_e32 v87, v9, v25
	v_fmac_f32_e32 v86, v10, v62
	v_fmac_f32_e32 v87, v11, v26
	v_cvt_pk_bf16_f32 v86, v86, v87
	ds_write_b32 v92, v86 offset:11440
	s_waitcnt vmcnt(19)
	v_lshlrev_b32_e32 v63, 16, v27
	v_and_b32_e32 v27, 0xffff0000, v27
	v_fma_f32 v84, v4, v60, v2
	v_fma_f32 v85, v5, v24, v3
	v_fmac_f32_e32 v84, v6, v61
	v_fmac_f32_e32 v85, v7, v25
	v_fmac_f32_e32 v84, v8, v62
	v_fmac_f32_e32 v85, v9, v26
	v_fmac_f32_e32 v84, v10, v63
	v_fmac_f32_e32 v85, v11, v27
	v_cvt_pk_bf16_f32 v84, v84, v85
	ds_write_b32 v92, v84 offset:12480
	s_waitcnt vmcnt(18)
	v_lshlrev_b32_e32 v64, 16, v28
	v_and_b32_e32 v28, 0xffff0000, v28
	v_fma_f32 v86, v4, v61, v2
	v_fma_f32 v87, v5, v25, v3
	v_fmac_f32_e32 v86, v6, v62
	v_fmac_f32_e32 v87, v7, v26
	v_fmac_f32_e32 v86, v8, v63
	v_fmac_f32_e32 v87, v9, v27
	v_fmac_f32_e32 v86, v10, v64
	v_fmac_f32_e32 v87, v11, v28
	v_cvt_pk_bf16_f32 v86, v86, v87
	ds_write_b32 v92, v86 offset:13520
	s_waitcnt vmcnt(17)
	v_lshlrev_b32_e32 v65, 16, v29
	v_and_b32_e32 v29, 0xffff0000, v29
	v_fma_f32 v84, v4, v62, v2
	v_fma_f32 v85, v5, v26, v3
	v_fmac_f32_e32 v84, v6, v63
	v_fmac_f32_e32 v85, v7, v27
	v_fmac_f32_e32 v84, v8, v64
	v_fmac_f32_e32 v85, v9, v28
	v_fmac_f32_e32 v84, v10, v65
	v_fmac_f32_e32 v85, v11, v29
	v_cvt_pk_bf16_f32 v84, v84, v85
	ds_write_b32 v92, v84 offset:14560
	s_waitcnt vmcnt(16)
	v_lshlrev_b32_e32 v66, 16, v30
	v_and_b32_e32 v30, 0xffff0000, v30
	v_fma_f32 v86, v4, v63, v2
	v_fma_f32 v87, v5, v27, v3
	v_fmac_f32_e32 v86, v6, v64
	v_fmac_f32_e32 v87, v7, v28
	v_fmac_f32_e32 v86, v8, v65
	v_fmac_f32_e32 v87, v9, v29
	v_fmac_f32_e32 v86, v10, v66
	v_fmac_f32_e32 v87, v11, v30
	v_cvt_pk_bf16_f32 v86, v86, v87
	ds_write_b32 v92, v86 offset:15600
	s_waitcnt vmcnt(15)
	v_lshlrev_b32_e32 v67, 16, v31
	v_and_b32_e32 v31, 0xffff0000, v31
	v_fma_f32 v84, v4, v64, v2
	v_fma_f32 v85, v5, v28, v3
	v_fmac_f32_e32 v84, v6, v65
	v_fmac_f32_e32 v85, v7, v29
	v_fmac_f32_e32 v84, v8, v66
	v_fmac_f32_e32 v85, v9, v30
	v_fmac_f32_e32 v84, v10, v67
	v_fmac_f32_e32 v85, v11, v31
	v_cvt_pk_bf16_f32 v84, v84, v85
	ds_write_b32 v92, v84 offset:16640
	s_waitcnt vmcnt(14)
; __device__ __forceinline__ float bf2f(bf16_t b) { return __uint_as_float(((unsigned)b) << 16); }
; __device__ __forceinline__ bf16_t f2bf(float f) { unsigned u = __float_as_uint(f); return (bf16_t)((u + 0x7fffu + ((u >> 16) & 1u)) >> 16); }
; template <int DIR> __device__ __forceinline__ void lru_dir(const Params& p, int l, int n, int h, int lane, LAS bf16_t* XC, LAS float* STA, LAS float* STU) {
;     ...
;     const float* lam = p.in[10] + (size_t)(l * 2 + DIR) * 512 + 64 * h; const float* b_a = p.in[7] + (size_t)(l * 2 + DIR) * 512 + 64 * h; const float* b_x = p.in[9] + (size_t)(l * 2 + DIR) * 512 + 64 * h;
;     const bf16_t* LWa = LW + ((size_t)(DIR * 2 + 0) * 8 + h) * 4096 + c * 64 + 8 * q; const bf16_t* LWx = LW + ((size_t)(DIR * 2 + 1) * 8 + h) * 4096 + c * 64 + 8 * q;
; template <int MODE> __device__ void mixer_lru(const Params& p, int l, int n, LAS unsigned char* lds) {
;     ...
;             for (int i = 0; i < 67; ++i) { const int s_ = t0 - 2 + i; const int sc = s_ < 0 ? 0 : (s_ >= S ? S - 1 : s_); const bf16_t v = proj[(size_t)sc * DINP + ch]; xs[i] = s_ == sc ? v : (bf16_t)0; }
; #pragma unroll
;             for (int t = 0; t < 64; ++t) { const float xc = cb + cw0 * bf2f(xs[t]) + cw1 * bf2f(xs[t + 1]) + cw2 * bf2f(xs[t + 2]) + cw3 * bf2f(xs[t + 3]); XC[t * 520 + ch] = f2bf(xc); }
;         }
;         __syncthreads();
;         lru_dir<0>(p, l, n, wave, lane, XC, STA, STU);
	v_lshlrev_b32_e32 v68, 16, v32
	v_and_b32_e32 v32, 0xffff0000, v32
	v_fma_f32 v86, v4, v65, v2
	v_fma_f32 v87, v5, v29, v3
	v_fmac_f32_e32 v86, v6, v66
	v_fmac_f32_e32 v87, v7, v30
	v_fmac_f32_e32 v86, v8, v67
	v_fmac_f32_e32 v87, v9, v31
	v_fmac_f32_e32 v86, v10, v68
	v_fmac_f32_e32 v87, v11, v32
	v_cvt_pk_bf16_f32 v86, v86, v87
	ds_write_b32 v92, v86 offset:17680
	s_waitcnt vmcnt(13)
	v_lshlrev_b32_e32 v69, 16, v33
	v_and_b32_e32 v33, 0xffff0000, v33
	v_fma_f32 v84, v4, v66, v2
	v_fma_f32 v85, v5, v30, v3
	v_fmac_f32_e32 v84, v6, v67
	v_fmac_f32_e32 v85, v7, v31
	v_fmac_f32_e32 v84, v8, v68
	v_fmac_f32_e32 v85, v9, v32
	v_fmac_f32_e32 v84, v10, v69
	v_fmac_f32_e32 v85, v11, v33
	v_cvt_pk_bf16_f32 v84, v84, v85
	ds_write_b32 v92, v84 offset:18720
	s_waitcnt vmcnt(12)
	v_lshlrev_b32_e32 v70, 16, v34
	v_and_b32_e32 v34, 0xffff0000, v34
	v_fma_f32 v86, v4, v67, v2
	v_fma_f32 v87, v5, v31, v3
	v_fmac_f32_e32 v86, v6, v68
	v_fmac_f32_e32 v87, v7, v32
	v_fmac_f32_e32 v86, v8, v69
	v_fmac_f32_e32 v87, v9, v33
	v_fmac_f32_e32 v86, v10, v70
	v_fmac_f32_e32 v87, v11, v34
	v_cvt_pk_bf16_f32 v86, v86, v87
	ds_write_b32 v92, v86 offset:19760
	s_waitcnt vmcnt(11)
	v_lshlrev_b32_e32 v71, 16, v35
	v_and_b32_e32 v35, 0xffff0000, v35
	v_fma_f32 v84, v4, v68, v2
	v_fma_f32 v85, v5, v32, v3
	v_fmac_f32_e32 v84, v6, v69
	v_fmac_f32_e32 v85, v7, v33
	v_fmac_f32_e32 v84, v8, v70
	v_fmac_f32_e32 v85, v9, v34
	v_fmac_f32_e32 v84, v10, v71
	v_fmac_f32_e32 v85, v11, v35
	v_cvt_pk_bf16_f32 v84, v84, v85
	ds_write_b32 v92, v84 offset:20800
	s_waitcnt vmcnt(10)
	v_lshlrev_b32_e32 v72, 16, v36
	v_and_b32_e32 v36, 0xffff0000, v36
	v_fma_f32 v86, v4, v69, v2
	v_fma_f32 v87, v5, v33, v3
	v_fmac_f32_e32 v86, v6, v70
	v_fmac_f32_e32 v87, v7, v34
	v_fmac_f32_e32 v86, v8, v71
	v_fmac_f32_e32 v87, v9, v35
	v_fmac_f32_e32 v86, v10, v72
	v_fmac_f32_e32 v87, v11, v36
	v_cvt_pk_bf16_f32 v86, v86, v87
	ds_write_b32 v92, v86 offset:21840
	s_waitcnt vmcnt(9)
	v_lshlrev_b32_e32 v73, 16, v37
	v_and_b32_e32 v37, 0xffff0000, v37
	v_fma_f32 v84, v4, v70, v2
	v_fma_f32 v85, v5, v34, v3
	v_fmac_f32_e32 v84, v6, v71
	v_fmac_f32_e32 v85, v7, v35
	v_fmac_f32_e32 v84, v8, v72
	v_fmac_f32_e32 v85, v9, v36
	v_fmac_f32_e32 v84, v10, v73
	v_fmac_f32_e32 v85, v11, v37
	v_cvt_pk_bf16_f32 v84, v84, v85
	ds_write_b32 v92, v84 offset:22880
	s_waitcnt vmcnt(8)
	v_lshlrev_b32_e32 v74, 16, v38
	v_and_b32_e32 v38, 0xffff0000, v38
	v_fma_f32 v86, v4, v71, v2
	v_fma_f32 v87, v5, v35, v3
	v_fmac_f32_e32 v86, v6, v72
	v_fmac_f32_e32 v87, v7, v36
	v_fmac_f32_e32 v86, v8, v73
	v_fmac_f32_e32 v87, v9, v37
	v_fmac_f32_e32 v86, v10, v74
	v_fmac_f32_e32 v87, v11, v38
	v_cvt_pk_bf16_f32 v86, v86, v87
	ds_write_b32 v92, v86 offset:23920
	s_waitcnt vmcnt(7)
	v_lshlrev_b32_e32 v75, 16, v39
	v_and_b32_e32 v39, 0xffff0000, v39
	v_fma_f32 v84, v4, v72, v2
	v_fma_f32 v85, v5, v36, v3
	v_fmac_f32_e32 v84, v6, v73
	v_fmac_f32_e32 v85, v7, v37
	v_fmac_f32_e32 v84, v8, v74
	v_fmac_f32_e32 v85, v9, v38
	v_fmac_f32_e32 v84, v10, v75
	v_fmac_f32_e32 v85, v11, v39
	v_cvt_pk_bf16_f32 v84, v84, v85
	ds_write_b32 v92, v84 offset:24960
	s_waitcnt vmcnt(6)
	v_lshlrev_b32_e32 v76, 16, v40
	v_and_b32_e32 v40, 0xffff0000, v40
	v_fma_f32 v86, v4, v73, v2
	v_fma_f32 v87, v5, v37, v3
	v_fmac_f32_e32 v86, v6, v74
	v_fmac_f32_e32 v87, v7, v38
	v_fmac_f32_e32 v86, v8, v75
	v_fmac_f32_e32 v87, v9, v39
	v_fmac_f32_e32 v86, v10, v76
	v_fmac_f32_e32 v87, v11, v40
	v_cvt_pk_bf16_f32 v86, v86, v87
	ds_write_b32 v92, v86 offset:26000
	s_waitcnt vmcnt(5)
	v_lshlrev_b32_e32 v77, 16, v41
	v_and_b32_e32 v41, 0xffff0000, v41
	v_fma_f32 v84, v4, v74, v2
	v_fma_f32 v85, v5, v38, v3
	v_fmac_f32_e32 v84, v6, v75
	v_fmac_f32_e32 v85, v7, v39
	v_fmac_f32_e32 v84, v8, v76
	v_fmac_f32_e32 v85, v9, v40
	v_fmac_f32_e32 v84, v10, v77
	v_fmac_f32_e32 v85, v11, v41
	v_cvt_pk_bf16_f32 v84, v84, v85
	ds_write_b32 v92, v84 offset:27040
	s_waitcnt vmcnt(4)
	v_lshlrev_b32_e32 v78, 16, v42
	v_and_b32_e32 v42, 0xffff0000, v42
	v_fma_f32 v86, v4, v75, v2
	v_fma_f32 v87, v5, v39, v3
	v_fmac_f32_e32 v86, v6, v76
	v_fmac_f32_e32 v87, v7, v40
	v_fmac_f32_e32 v86, v8, v77
	v_fmac_f32_e32 v87, v9, v41
	v_fmac_f32_e32 v86, v10, v78
	v_fmac_f32_e32 v87, v11, v42
	v_cvt_pk_bf16_f32 v86, v86, v87
	ds_write_b32 v92, v86 offset:28080
	s_waitcnt vmcnt(3)
	v_lshlrev_b32_e32 v79, 16, v43
	v_and_b32_e32 v43, 0xffff0000, v43
	v_fma_f32 v84, v4, v76, v2
	v_fma_f32 v85, v5, v40, v3
	v_fmac_f32_e32 v84, v6, v77
	v_fmac_f32_e32 v85, v7, v41
	v_fmac_f32_e32 v84, v8, v78
	v_fmac_f32_e32 v85, v9, v42
	v_fmac_f32_e32 v84, v10, v79
	v_fmac_f32_e32 v85, v11, v43
	v_cvt_pk_bf16_f32 v84, v84, v85
	ds_write_b32 v92, v84 offset:29120
	s_waitcnt vmcnt(2)
	v_lshlrev_b32_e32 v80, 16, v44
	v_and_b32_e32 v44, 0xffff0000, v44
	v_fma_f32 v86, v4, v77, v2
	v_fma_f32 v87, v5, v41, v3
	v_fmac_f32_e32 v86, v6, v78
	v_fmac_f32_e32 v87, v7, v42
	v_fmac_f32_e32 v86, v8, v79
	v_fmac_f32_e32 v87, v9, v43
	v_fmac_f32_e32 v86, v10, v80
	v_fmac_f32_e32 v87, v11, v44
	v_cvt_pk_bf16_f32 v86, v86, v87
	ds_write_b32 v92, v86 offset:30160
	s_waitcnt vmcnt(1)
	v_lshlrev_b32_e32 v81, 16, v45
	v_and_b32_e32 v45, 0xffff0000, v45
	v_fma_f32 v84, v4, v78, v2
	v_fma_f32 v85, v5, v42, v3
	v_fmac_f32_e32 v84, v6, v79
	v_fmac_f32_e32 v85, v7, v43
	v_fmac_f32_e32 v84, v8, v80
	v_fmac_f32_e32 v85, v9, v44
	v_fmac_f32_e32 v84, v10, v81
	v_fmac_f32_e32 v85, v11, v45
	v_cvt_pk_bf16_f32 v84, v84, v85
	ds_write_b32 v92, v84 offset:31200
	s_waitcnt vmcnt(0)
	v_and_b32_e32 v46, s94, v46
	v_lshlrev_b32_e32 v82, 16, v46
	v_and_b32_e32 v46, 0xffff0000, v46
	v_fma_f32 v86, v4, v79, v2
	v_fma_f32 v87, v5, v43, v3
	v_fmac_f32_e32 v86, v6, v80
	v_fmac_f32_e32 v87, v7, v44
	v_fmac_f32_e32 v86, v8, v81
	v_fmac_f32_e32 v87, v9, v45
	v_fmac_f32_e32 v86, v10, v82
	v_fmac_f32_e32 v87, v11, v46
	v_cvt_pk_bf16_f32 v86, v86, v87
	ds_write_b32 v92, v86 offset:32240
	v_ashrrev_i32_e32 v102, 6, v100
	v_ashrrev_i32_e32 v103, 31, v102
	v_and_b32_e32 v127, 15, v100
	v_and_b32_e32 v124, 0xffffffc0, v100
	v_ashrrev_i32_e32 v125, 31, v124
	v_lshlrev_b32_e32 v176, 7, v127
	v_readlane_b32 s0, v254, 17
	v_lshlrev_b64 v[6:7], 13, v[102:103]
	v_readlane_b32 s1, v254, 18
	s_nop 1
	v_lshlrev_b64 v[112:113], 2, v[124:125]
	v_lshl_add_u64 v[114:115], s[0:1], 0, v[6:7]
	v_lshl_add_u64 v[6:7], v[114:115], 0, v[176:177]
	v_and_b32_e32 v176, 48, v100
	v_lshl_add_u64 v[0:1], s[16:17], 0, v[112:113]
	v_lshl_add_u64 v[80:81], v[6:7], 0, v[176:177]
	v_lshl_add_u64 v[76:77], v[0:1], 0, v[176:177]
	v_add_co_u32_e32 v0, vcc, 0x10000, v80
	v_lshl_add_u64 v[2:3], s[18:19], 0, v[112:113]
	v_lshl_add_u64 v[4:5], s[20:21], 0, v[112:113]
	s_mov_b64 s[0:1], 0x10000
	v_addc_co_u32_e32 v1, vcc, 0, v81, vcc
	s_waitcnt lgkmcnt(0)
	s_barrier
; template <int DIR> __device__ __forceinline__ void lru_dir(const Params& p, int l, int n, int h, int lane, LAS bf16_t* XC, LAS float* STA, LAS float* STU) {
;     ...
;     bf16x8 wa[4][2], wx[4][2]; f32x4 sp4[4], ba4[4], bx4[4];
; #pragma unroll
;     for (int nf = 0; nf < 4; ++nf) {
; #pragma unroll
;         for (int ks = 0; ks < 2; ++ks) { wa[nf][ks] = *(const bf16x8*)(LWa + nf * 1024 + 32 * ks); wx[nf][ks] = *(const bf16x8*)(LWx + nf * 1024 + 32 * ks); }
;         const f32x4 lam4 = *(const f32x4*)(lam + 16 * nf + 4 * q); ba4[nf] = *(const f32x4*)(b_a + 16 * nf + 4 * q); bx4[nf] = *(const f32x4*)(b_x + 16 * nf + 4 * q);
; #pragma unroll
;         for (int r = 0; r < 4; ++r) { const float e = __expf(-lam4[r]); const float l1p = e < 0.05f ? e * (1.0f - e * (0.5f - e * (0.33333334f - e * 0.25f))) : __logf(1.0f + e); sp4[nf][r] = -8.0f * l1p; }
;     }
	v_lshl_add_u64 v[78:79], v[80:81], 0, s[0:1]
	v_lshl_add_u64 v[88:89], v[2:3], 0, v[176:177]
	v_lshl_add_u64 v[92:93], v[4:5], 0, v[176:177]
	global_load_dwordx4 v[192:195], v[76:77], off
	global_load_dwordx4 v[196:199], v[76:77], off offset:64
	global_load_dwordx4 v[200:203], v[76:77], off offset:128
	global_load_dwordx4 v[204:207], v[76:77], off offset:192
	s_nop 0
	global_load_dwordx4 v[0:3], v[0:1], off
	s_nop 0
	global_load_dwordx4 v[4:7], v[80:81], off
	global_load_dwordx4 v[8:11], v[80:81], off offset:64
	global_load_dwordx4 v[12:15], v[78:79], off offset:64
	global_load_dwordx4 v[16:19], v[88:89], off
	global_load_dwordx4 v[20:23], v[92:93], off
	s_mov_b32 s6, 0x3d4ccccd
	s_waitcnt vmcnt(6)
	v_mul_f32_e32 v24, 0xbfb8aa3b, v192
	v_exp_f32_e32 v24, v24
	s_nop 0
	v_cmp_ngt_f32_e32 vcc, s6, v24
	s_and_saveexec_b64 s[0:1], vcc
	s_xor_b64 s[30:31], exec, s[0:1]
	s_cbranch_execz .LBB0_194
	v_add_f32_e32 v24, 1.0, v24
	v_cmp_gt_f32_e32 vcc, s25, v24
	s_nop 1
	v_cndmask_b32_e64 v28, 0, 32, vcc
	v_ldexp_f32 v24, v24, v28
	v_log_f32_e32 v24, v24
	s_nop 0
	v_mul_f32_e32 v28, 0x3f317217, v24
	v_fma_f32 v28, v24, s36, -v28
	v_fmac_f32_e32 v28, 0x3377d1cf, v24
	v_fmac_f32_e32 v28, 0x3f317217, v24
	v_cmp_lt_f32_e64 s[0:1], |v24|, s37
	s_nop 1
	v_cndmask_b32_e64 v24, v24, v28, s[0:1]
	v_cndmask_b32_e32 v28, 0, v232, vcc
	v_sub_f32_e32 v101, v24, v28
.LBB0_194:
	s_andn2_saveexec_b64 s[0:1], s[30:31]
	v_fmamk_f32 v28, v24, 0xbe800000, v226
	v_fma_f32 v28, -v24, v28, 0.5
	v_fma_f32 v28, -v24, v28, 1.0
	v_mul_f32_e32 v101, v24, v28
	s_or_b64 exec, exec, s[0:1]
	v_mul_f32_e32 v24, 0xbfb8aa3b, v193
	v_exp_f32_e32 v24, v24
	s_nop 0
	v_cmp_ngt_f32_e32 vcc, s6, v24
	s_and_saveexec_b64 s[0:1], vcc
	v_readlane_b32 s52, v254, 60
	s_xor_b64 s[30:31], exec, s[0:1]
	v_readlane_b32 s56, v255, 0
	v_readlane_b32 s57, v255, 1
	s_mov_b32 s2, 0x1858000
	s_movk_i32 s7, 0x410
	v_readlane_b32 s53, v254, 61
	v_readlane_b32 s54, v254, 62
	v_readlane_b32 s55, v254, 63
	v_readlane_b32 s58, v255, 2
	v_readlane_b32 s59, v255, 3
	s_cbranch_execz .LBB0_198
	v_add_f32_e32 v24, 1.0, v24
	v_cmp_gt_f32_e32 vcc, s25, v24
	s_nop 1
	v_cndmask_b32_e64 v25, 0, 32, vcc
	v_ldexp_f32 v24, v24, v25
	v_log_f32_e32 v24, v24
	s_nop 0
	v_mul_f32_e32 v25, 0x3f317217, v24
	v_fma_f32 v25, v24, s36, -v25
	v_fmac_f32_e32 v25, 0x3377d1cf, v24
	v_fmac_f32_e32 v25, 0x3f317217, v24
	v_cmp_lt_f32_e64 s[0:1], |v24|, s37
	s_nop 1
	v_cndmask_b32_e64 v24, v24, v25, s[0:1]
	v_cndmask_b32_e32 v25, 0, v232, vcc
	v_sub_f32_e32 v103, v24, v25
.LBB0_198:
	s_andn2_saveexec_b64 s[0:1], s[30:31]
	v_fmamk_f32 v25, v24, 0xbe800000, v226
	v_fma_f32 v25, -v24, v25, 0.5
	v_fma_f32 v25, -v24, v25, 1.0
	v_mul_f32_e32 v103, v24, v25
	s_or_b64 exec, exec, s[0:1]
	v_mul_f32_e32 v24, 0xbfb8aa3b, v194
	v_exp_f32_e32 v24, v24
	s_nop 0
	v_cmp_ngt_f32_e32 vcc, s6, v24
	s_and_saveexec_b64 s[0:1], vcc
	s_xor_b64 s[30:31], exec, s[0:1]
	s_cbranch_execz .LBB0_202
	v_add_f32_e32 v24, 1.0, v24
	v_cmp_gt_f32_e32 vcc, s25, v24
	s_nop 1
	v_cndmask_b32_e64 v25, 0, 32, vcc
	v_ldexp_f32 v24, v24, v25
	v_log_f32_e32 v24, v24
	s_nop 0
	v_mul_f32_e32 v25, 0x3f317217, v24
	v_fma_f32 v25, v24, s36, -v25
	v_fmac_f32_e32 v25, 0x3377d1cf, v24
	v_fmac_f32_e32 v25, 0x3f317217, v24
	v_cmp_lt_f32_e64 s[0:1], |v24|, s37
	s_nop 1
	v_cndmask_b32_e64 v24, v24, v25, s[0:1]
	v_cndmask_b32_e32 v25, 0, v232, vcc
	v_sub_f32_e32 v104, v24, v25
.LBB0_202:
	s_andn2_saveexec_b64 s[0:1], s[30:31]
	v_fmamk_f32 v25, v24, 0xbe800000, v226
	v_fma_f32 v25, -v24, v25, 0.5
	v_fma_f32 v25, -v24, v25, 1.0
	v_mul_f32_e32 v104, v24, v25
	s_or_b64 exec, exec, s[0:1]
	v_mul_f32_e32 v24, 0xbfb8aa3b, v195
	v_exp_f32_e32 v24, v24
	s_nop 0
	v_cmp_ngt_f32_e32 vcc, s6, v24
	s_and_saveexec_b64 s[0:1], vcc
	s_xor_b64 s[30:31], exec, s[0:1]
	s_cbranch_execz .LBB0_206
	v_add_f32_e32 v24, 1.0, v24
	v_cmp_gt_f32_e32 vcc, s25, v24
	s_nop 1
	v_cndmask_b32_e64 v25, 0, 32, vcc
	v_ldexp_f32 v24, v24, v25
	v_log_f32_e32 v24, v24
	s_nop 0
	v_mul_f32_e32 v25, 0x3f317217, v24
	v_fma_f32 v25, v24, s36, -v25
	v_fmac_f32_e32 v25, 0x3377d1cf, v24
	v_fmac_f32_e32 v25, 0x3f317217, v24
	v_cmp_lt_f32_e64 s[0:1], |v24|, s37
	s_nop 1
	v_cndmask_b32_e64 v24, v24, v25, s[0:1]
	v_cndmask_b32_e32 v25, 0, v232, vcc
	v_sub_f32_e32 v105, v24, v25
.LBB0_206:
	s_andn2_saveexec_b64 s[0:1], s[30:31]
	v_fmamk_f32 v25, v24, 0xbe800000, v226
	v_fma_f32 v25, -v24, v25, 0.5
	v_fma_f32 v25, -v24, v25, 1.0
	v_mul_f32_e32 v105, v24, v25
	s_or_b64 exec, exec, s[0:1]
	global_load_dwordx4 v[24:27], v[80:81], off offset:2048
	global_load_dwordx4 v[28:31], v[80:81], off offset:2112
	global_load_dwordx4 v[32:35], v[78:79], off offset:2048
	global_load_dwordx4 v[36:39], v[78:79], off offset:2112
	global_load_dwordx4 v[40:43], v[88:89], off offset:64
	global_load_dwordx4 v[44:47], v[92:93], off offset:64
	v_mul_f32_e32 v48, 0xbfb8aa3b, v196
	v_exp_f32_e32 v48, v48
	s_nop 0
	v_cmp_ngt_f32_e32 vcc, s6, v48
	s_and_saveexec_b64 s[0:1], vcc
	s_xor_b64 s[30:31], exec, s[0:1]
	s_cbranch_execz .LBB0_210
	v_add_f32_e32 v48, 1.0, v48
	v_cmp_gt_f32_e32 vcc, s25, v48
	s_nop 1
	v_cndmask_b32_e64 v52, 0, 32, vcc
	v_ldexp_f32 v48, v48, v52
	v_log_f32_e32 v48, v48
	s_nop 0
	v_mul_f32_e32 v52, 0x3f317217, v48
	v_fma_f32 v52, v48, s36, -v52
	v_fmac_f32_e32 v52, 0x3377d1cf, v48
	v_fmac_f32_e32 v52, 0x3f317217, v48
	v_cmp_lt_f32_e64 s[0:1], |v48|, s37
	s_nop 1
	v_cndmask_b32_e64 v48, v48, v52, s[0:1]
	v_cndmask_b32_e32 v52, 0, v232, vcc
	v_sub_f32_e32 v106, v48, v52
; template <int DIR> __device__ __forceinline__ void lru_dir(const Params& p, int l, int n, int h, int lane, LAS bf16_t* XC, LAS float* STA, LAS float* STU) {
;     ...
;     for (int nf = 0; nf < 4; ++nf) {
; #pragma unroll
;         for (int ks = 0; ks < 2; ++ks) { wa[nf][ks] = *(const bf16x8*)(LWa + nf * 1024 + 32 * ks); wx[nf][ks] = *(const bf16x8*)(LWx + nf * 1024 + 32 * ks); }
;         const f32x4 lam4 = *(const f32x4*)(lam + 16 * nf + 4 * q); ba4[nf] = *(const f32x4*)(b_a + 16 * nf + 4 * q); bx4[nf] = *(const f32x4*)(b_x + 16 * nf + 4 * q);
; #pragma unroll
;         for (int r = 0; r < 4; ++r) { const float e = __expf(-lam4[r]); const float l1p = e < 0.05f ? e * (1.0f - e * (0.5f - e * (0.33333334f - e * 0.25f))) : __logf(1.0f + e); sp4[nf][r] = -8.0f * l1p; }
;     }
.LBB0_210:
	s_andn2_saveexec_b64 s[0:1], s[30:31]
	v_fmamk_f32 v52, v48, 0xbe800000, v226
	v_fma_f32 v52, -v48, v52, 0.5
	v_fma_f32 v52, -v48, v52, 1.0
	v_mul_f32_e32 v106, v48, v52
	s_or_b64 exec, exec, s[0:1]
	v_mul_f32_e32 v48, 0xbfb8aa3b, v197
	v_exp_f32_e32 v48, v48
	s_nop 0
	v_cmp_ngt_f32_e32 vcc, s6, v48
	s_and_saveexec_b64 s[0:1], vcc
	s_xor_b64 s[30:31], exec, s[0:1]
	s_cbranch_execz .LBB0_214
	v_add_f32_e32 v48, 1.0, v48
	v_cmp_gt_f32_e32 vcc, s25, v48
	s_nop 1
	v_cndmask_b32_e64 v49, 0, 32, vcc
	v_ldexp_f32 v48, v48, v49
	v_log_f32_e32 v48, v48
	s_nop 0
	v_mul_f32_e32 v49, 0x3f317217, v48
	v_fma_f32 v49, v48, s36, -v49
	v_fmac_f32_e32 v49, 0x3377d1cf, v48
	v_fmac_f32_e32 v49, 0x3f317217, v48
	v_cmp_lt_f32_e64 s[0:1], |v48|, s37
	s_nop 1
	v_cndmask_b32_e64 v48, v48, v49, s[0:1]
	v_cndmask_b32_e32 v49, 0, v232, vcc
	v_sub_f32_e32 v107, v48, v49
.LBB0_214:
	s_andn2_saveexec_b64 s[0:1], s[30:31]
	v_fmamk_f32 v49, v48, 0xbe800000, v226
	v_fma_f32 v49, -v48, v49, 0.5
	v_fma_f32 v49, -v48, v49, 1.0
	v_mul_f32_e32 v107, v48, v49
	s_or_b64 exec, exec, s[0:1]
	v_mul_f32_e32 v48, 0xbfb8aa3b, v198
	v_exp_f32_e32 v48, v48
	s_nop 0
	v_cmp_ngt_f32_e32 vcc, s6, v48
	s_and_saveexec_b64 s[0:1], vcc
	s_xor_b64 s[30:31], exec, s[0:1]
	s_cbranch_execz .LBB0_218
	v_add_f32_e32 v48, 1.0, v48
	v_cmp_gt_f32_e32 vcc, s25, v48
	s_nop 1
	v_cndmask_b32_e64 v49, 0, 32, vcc
	v_ldexp_f32 v48, v48, v49
	v_log_f32_e32 v48, v48
	s_nop 0
	v_mul_f32_e32 v49, 0x3f317217, v48
	v_fma_f32 v49, v48, s36, -v49
	v_fmac_f32_e32 v49, 0x3377d1cf, v48
	v_fmac_f32_e32 v49, 0x3f317217, v48
	v_cmp_lt_f32_e64 s[0:1], |v48|, s37
	s_nop 1
	v_cndmask_b32_e64 v48, v48, v49, s[0:1]
	v_cndmask_b32_e32 v49, 0, v232, vcc
	v_sub_f32_e32 v108, v48, v49
.LBB0_218:
	s_andn2_saveexec_b64 s[0:1], s[30:31]
	v_fmamk_f32 v49, v48, 0xbe800000, v226
	v_fma_f32 v49, -v48, v49, 0.5
	v_fma_f32 v49, -v48, v49, 1.0
	v_mul_f32_e32 v108, v48, v49
	s_or_b64 exec, exec, s[0:1]
	v_mul_f32_e32 v48, 0xbfb8aa3b, v199
	v_exp_f32_e32 v48, v48
	s_nop 0
	v_cmp_ngt_f32_e32 vcc, s6, v48
	s_and_saveexec_b64 s[0:1], vcc
	s_xor_b64 s[30:31], exec, s[0:1]
	s_cbranch_execz .LBB0_222
	v_add_f32_e32 v48, 1.0, v48
	v_cmp_gt_f32_e32 vcc, s25, v48
	s_nop 1
	v_cndmask_b32_e64 v49, 0, 32, vcc
	v_ldexp_f32 v48, v48, v49
	v_log_f32_e32 v48, v48
	s_nop 0
	v_mul_f32_e32 v49, 0x3f317217, v48
	v_fma_f32 v49, v48, s36, -v49
	v_fmac_f32_e32 v49, 0x3377d1cf, v48
	v_fmac_f32_e32 v49, 0x3f317217, v48
	v_cmp_lt_f32_e64 s[0:1], |v48|, s37
	s_nop 1
	v_cndmask_b32_e64 v48, v48, v49, s[0:1]
	v_cndmask_b32_e32 v49, 0, v232, vcc
	v_sub_f32_e32 v109, v48, v49
.LBB0_222:
	s_andn2_saveexec_b64 s[0:1], s[30:31]
	v_fmamk_f32 v49, v48, 0xbe800000, v226
	v_fma_f32 v49, -v48, v49, 0.5
	v_fma_f32 v49, -v48, v49, 1.0
	v_mul_f32_e32 v109, v48, v49
	s_or_b64 exec, exec, s[0:1]
	v_add_co_u32_e32 v52, vcc, 0x1000, v80
	s_nop 1
	v_addc_co_u32_e32 v53, vcc, 0, v81, vcc
	v_add_co_u32_e32 v60, vcc, 0x1000, v78
	s_nop 1
	v_addc_co_u32_e32 v61, vcc, 0, v79, vcc
	global_load_dwordx4 v[48:51], v[52:53], off
	s_nop 0
	global_load_dwordx4 v[52:55], v[52:53], off offset:64
	s_nop 0
	global_load_dwordx4 v[56:59], v[60:61], off
	s_nop 0
	global_load_dwordx4 v[60:63], v[60:61], off offset:64
	s_nop 0
	global_load_dwordx4 v[64:67], v[88:89], off offset:128
	global_load_dwordx4 v[68:71], v[92:93], off offset:128
	v_mul_f32_e32 v72, 0xbfb8aa3b, v200
	v_exp_f32_e32 v72, v72
	s_nop 0
	v_cmp_ngt_f32_e32 vcc, s6, v72
	s_and_saveexec_b64 s[0:1], vcc
	s_xor_b64 s[30:31], exec, s[0:1]
	s_cbranch_execz .LBB0_226
	v_add_f32_e32 v72, 1.0, v72
	v_cmp_gt_f32_e32 vcc, s25, v72
	s_nop 1
	v_cndmask_b32_e64 v82, 0, 32, vcc
	v_ldexp_f32 v72, v72, v82
	v_log_f32_e32 v72, v72
	s_nop 0
	v_mul_f32_e32 v82, 0x3f317217, v72
	v_fma_f32 v82, v72, s36, -v82
	v_fmac_f32_e32 v82, 0x3377d1cf, v72
	v_fmac_f32_e32 v82, 0x3f317217, v72
	v_cmp_lt_f32_e64 s[0:1], |v72|, s37
	s_nop 1
	v_cndmask_b32_e64 v72, v72, v82, s[0:1]
	v_cndmask_b32_e32 v82, 0, v232, vcc
	v_sub_f32_e32 v110, v72, v82
.LBB0_226:
	s_andn2_saveexec_b64 s[0:1], s[30:31]
	v_fmamk_f32 v82, v72, 0xbe800000, v226
	v_fma_f32 v82, -v72, v82, 0.5
	v_fma_f32 v82, -v72, v82, 1.0
	v_mul_f32_e32 v110, v72, v82
	s_or_b64 exec, exec, s[0:1]
	v_mul_f32_e32 v72, 0xbfb8aa3b, v201
	v_exp_f32_e32 v72, v72
	s_nop 0
	v_cmp_ngt_f32_e32 vcc, s6, v72
	s_and_saveexec_b64 s[0:1], vcc
	s_xor_b64 s[30:31], exec, s[0:1]
	s_cbranch_execz .LBB0_230
	v_add_f32_e32 v72, 1.0, v72
	v_cmp_gt_f32_e32 vcc, s25, v72
	s_nop 1
	v_cndmask_b32_e64 v73, 0, 32, vcc
	v_ldexp_f32 v72, v72, v73
	v_log_f32_e32 v72, v72
	s_nop 0
	v_mul_f32_e32 v73, 0x3f317217, v72
	v_fma_f32 v73, v72, s36, -v73
	v_fmac_f32_e32 v73, 0x3377d1cf, v72
	v_fmac_f32_e32 v73, 0x3f317217, v72
	v_cmp_lt_f32_e64 s[0:1], |v72|, s37
	s_nop 1
	v_cndmask_b32_e64 v72, v72, v73, s[0:1]
	v_cndmask_b32_e32 v73, 0, v232, vcc
	v_sub_f32_e32 v111, v72, v73
.LBB0_230:
	s_andn2_saveexec_b64 s[0:1], s[30:31]
	v_fmamk_f32 v73, v72, 0xbe800000, v226
	v_fma_f32 v73, -v72, v73, 0.5
	v_fma_f32 v73, -v72, v73, 1.0
	v_mul_f32_e32 v111, v72, v73
	s_or_b64 exec, exec, s[0:1]
	v_mul_f32_e32 v72, 0xbfb8aa3b, v202
	v_exp_f32_e32 v72, v72
	s_nop 0
	v_cmp_ngt_f32_e32 vcc, s6, v72
	s_and_saveexec_b64 s[0:1], vcc
	s_xor_b64 s[30:31], exec, s[0:1]
	s_cbranch_execz .LBB0_234
	v_add_f32_e32 v72, 1.0, v72
	v_cmp_gt_f32_e32 vcc, s25, v72
	s_nop 1
	v_cndmask_b32_e64 v73, 0, 32, vcc
	v_ldexp_f32 v72, v72, v73
	v_log_f32_e32 v72, v72
	s_nop 0
	v_mul_f32_e32 v73, 0x3f317217, v72
	v_fma_f32 v73, v72, s36, -v73
	v_fmac_f32_e32 v73, 0x3377d1cf, v72
	v_fmac_f32_e32 v73, 0x3f317217, v72
	v_cmp_lt_f32_e64 s[0:1], |v72|, s37
	s_nop 1
	v_cndmask_b32_e64 v72, v72, v73, s[0:1]
	v_cndmask_b32_e32 v73, 0, v232, vcc
	v_sub_f32_e32 v116, v72, v73
; template <int DIR> __device__ __forceinline__ void lru_dir(const Params& p, int l, int n, int h, int lane, LAS bf16_t* XC, LAS float* STA, LAS float* STU) {
;     ...
;     for (int nf = 0; nf < 4; ++nf) {
; #pragma unroll
;         for (int ks = 0; ks < 2; ++ks) { wa[nf][ks] = *(const bf16x8*)(LWa + nf * 1024 + 32 * ks); wx[nf][ks] = *(const bf16x8*)(LWx + nf * 1024 + 32 * ks); }
;         const f32x4 lam4 = *(const f32x4*)(lam + 16 * nf + 4 * q); ba4[nf] = *(const f32x4*)(b_a + 16 * nf + 4 * q); bx4[nf] = *(const f32x4*)(b_x + 16 * nf + 4 * q);
; #pragma unroll
;         for (int r = 0; r < 4; ++r) { const float e = __expf(-lam4[r]); const float l1p = e < 0.05f ? e * (1.0f - e * (0.5f - e * (0.33333334f - e * 0.25f))) : __logf(1.0f + e); sp4[nf][r] = -8.0f * l1p; }
;     }
.LBB0_234:
	s_andn2_saveexec_b64 s[0:1], s[30:31]
	v_fmamk_f32 v73, v72, 0xbe800000, v226
	v_fma_f32 v73, -v72, v73, 0.5
	v_fma_f32 v73, -v72, v73, 1.0
	v_mul_f32_e32 v116, v72, v73
	s_or_b64 exec, exec, s[0:1]
	v_mul_f32_e32 v72, 0xbfb8aa3b, v203
	v_exp_f32_e32 v72, v72
	s_nop 0
	v_cmp_ngt_f32_e32 vcc, s6, v72
	s_and_saveexec_b64 s[0:1], vcc
	s_xor_b64 s[30:31], exec, s[0:1]
	s_cbranch_execz .LBB0_238
	v_add_f32_e32 v72, 1.0, v72
	v_cmp_gt_f32_e32 vcc, s25, v72
	s_nop 1
	v_cndmask_b32_e64 v73, 0, 32, vcc
	v_ldexp_f32 v72, v72, v73
	v_log_f32_e32 v72, v72
	s_nop 0
	v_mul_f32_e32 v73, 0x3f317217, v72
	v_fma_f32 v73, v72, s36, -v73
	v_fmac_f32_e32 v73, 0x3377d1cf, v72
	v_fmac_f32_e32 v73, 0x3f317217, v72
	v_cmp_lt_f32_e64 s[0:1], |v72|, s37
	s_nop 1
	v_cndmask_b32_e64 v72, v72, v73, s[0:1]
	v_cndmask_b32_e32 v73, 0, v232, vcc
	v_sub_f32_e32 v117, v72, v73
.LBB0_238:
	s_andn2_saveexec_b64 s[0:1], s[30:31]
	v_fmamk_f32 v73, v72, 0xbe800000, v226
	v_fma_f32 v73, -v72, v73, 0.5
	v_fma_f32 v73, -v72, v73, 1.0
	v_mul_f32_e32 v117, v72, v73
	s_or_b64 exec, exec, s[0:1]
	v_add_co_u32_e32 v80, vcc, 0x1000, v80
	s_nop 1
	v_addc_co_u32_e32 v81, vcc, 0, v81, vcc
	v_add_co_u32_e32 v84, vcc, 0x1000, v78
	s_nop 1
	v_addc_co_u32_e32 v85, vcc, 0, v79, vcc
	global_load_dwordx4 v[72:75], v[80:81], off offset:2048
	s_nop 0
	global_load_dwordx4 v[76:79], v[80:81], off offset:2112
	s_nop 0
	global_load_dwordx4 v[80:83], v[84:85], off offset:2048
	s_nop 0
	global_load_dwordx4 v[84:87], v[84:85], off offset:2112
	s_nop 0
	global_load_dwordx4 v[88:91], v[88:89], off offset:192
	s_nop 0
	global_load_dwordx4 v[92:95], v[92:93], off offset:192
	v_mul_f32_e32 v96, 0xbfb8aa3b, v204
	v_exp_f32_e32 v118, v96
	s_nop 0
	v_cmp_ngt_f32_e32 vcc, s6, v118
	s_and_saveexec_b64 s[0:1], vcc
	s_xor_b64 s[30:31], exec, s[0:1]
	s_cbranch_execz .LBB0_242
	v_add_f32_e32 v96, 1.0, v118
	v_cmp_gt_f32_e32 vcc, s25, v96
	s_nop 1
	v_cndmask_b32_e64 v118, 0, 32, vcc
	v_ldexp_f32 v96, v96, v118
	v_log_f32_e32 v96, v96
	s_nop 0
	v_mul_f32_e32 v118, 0x3f317217, v96
	v_fma_f32 v118, v96, s36, -v118
	v_fmac_f32_e32 v118, 0x3377d1cf, v96
	v_fmac_f32_e32 v118, 0x3f317217, v96
	v_cmp_lt_f32_e64 s[0:1], |v96|, s37
	s_nop 1
	v_cndmask_b32_e64 v96, v96, v118, s[0:1]
	v_cndmask_b32_e32 v118, 0, v232, vcc
	v_sub_f32_e32 v96, v96, v118
.LBB0_242:
	s_andn2_saveexec_b64 s[0:1], s[30:31]
	v_fmamk_f32 v96, v118, 0xbe800000, v226
	v_fma_f32 v96, -v118, v96, 0.5
	v_fma_f32 v96, -v118, v96, 1.0
	v_mul_f32_e32 v96, v118, v96
	s_or_b64 exec, exec, s[0:1]
	v_mul_f32_e32 v97, 0xbfb8aa3b, v205
	v_exp_f32_e32 v118, v97
	s_nop 0
	v_cmp_ngt_f32_e32 vcc, s6, v118
	s_and_saveexec_b64 s[0:1], vcc
	s_xor_b64 s[30:31], exec, s[0:1]
	s_cbranch_execz .LBB0_246
	v_add_f32_e32 v97, 1.0, v118
	v_cmp_gt_f32_e32 vcc, s25, v97
	s_nop 1
	v_cndmask_b32_e64 v118, 0, 32, vcc
	v_ldexp_f32 v97, v97, v118
	v_log_f32_e32 v97, v97
	s_nop 0
	v_mul_f32_e32 v118, 0x3f317217, v97
	v_fma_f32 v118, v97, s36, -v118
	v_fmac_f32_e32 v118, 0x3377d1cf, v97
	v_fmac_f32_e32 v118, 0x3f317217, v97
	v_cmp_lt_f32_e64 s[0:1], |v97|, s37
	s_nop 1
	v_cndmask_b32_e64 v97, v97, v118, s[0:1]
	v_cndmask_b32_e32 v118, 0, v232, vcc
	v_sub_f32_e32 v97, v97, v118
.LBB0_246:
	s_andn2_saveexec_b64 s[0:1], s[30:31]
	v_fmamk_f32 v97, v118, 0xbe800000, v226
	v_fma_f32 v97, -v118, v97, 0.5
	v_fma_f32 v97, -v118, v97, 1.0
	v_mul_f32_e32 v97, v118, v97
	s_or_b64 exec, exec, s[0:1]
	v_mul_f32_e32 v98, 0xbfb8aa3b, v206
	v_exp_f32_e32 v118, v98
	s_nop 0
	v_cmp_ngt_f32_e32 vcc, s6, v118
	s_and_saveexec_b64 s[0:1], vcc
	s_xor_b64 s[30:31], exec, s[0:1]
	s_cbranch_execz .LBB0_250
	v_add_f32_e32 v98, 1.0, v118
	v_cmp_gt_f32_e32 vcc, s25, v98
	s_nop 1
	v_cndmask_b32_e64 v118, 0, 32, vcc
	v_ldexp_f32 v98, v98, v118
	v_log_f32_e32 v98, v98
	s_nop 0
	v_mul_f32_e32 v118, 0x3f317217, v98
	v_fma_f32 v118, v98, s36, -v118
	v_fmac_f32_e32 v118, 0x3377d1cf, v98
	v_fmac_f32_e32 v118, 0x3f317217, v98
	v_cmp_lt_f32_e64 s[0:1], |v98|, s37
	s_nop 1
	v_cndmask_b32_e64 v98, v98, v118, s[0:1]
	v_cndmask_b32_e32 v118, 0, v232, vcc
	v_sub_f32_e32 v98, v98, v118
.LBB0_250:
	s_andn2_saveexec_b64 s[0:1], s[30:31]
	v_fmamk_f32 v98, v118, 0xbe800000, v226
	v_fma_f32 v98, -v118, v98, 0.5
	v_fma_f32 v98, -v118, v98, 1.0
	v_mul_f32_e32 v98, v118, v98
	s_or_b64 exec, exec, s[0:1]
	v_mul_f32_e32 v99, 0xbfb8aa3b, v207
	v_exp_f32_e32 v118, v99
	s_nop 0
	v_cmp_ngt_f32_e32 vcc, s6, v118
	s_and_saveexec_b64 s[0:1], vcc
	s_xor_b64 s[30:31], exec, s[0:1]
	s_cbranch_execz .LBB0_254
	v_add_f32_e32 v99, 1.0, v118
	v_cmp_gt_f32_e32 vcc, s25, v99
	s_nop 1
	v_cndmask_b32_e64 v118, 0, 32, vcc
	v_ldexp_f32 v99, v99, v118
	v_log_f32_e32 v99, v99
	s_nop 0
	v_mul_f32_e32 v118, 0x3f317217, v99
	v_fma_f32 v118, v99, s36, -v118
	v_fmac_f32_e32 v118, 0x3377d1cf, v99
	v_fmac_f32_e32 v118, 0x3f317217, v99
	v_cmp_lt_f32_e64 s[0:1], |v99|, s37
	s_nop 1
	v_cndmask_b32_e64 v99, v99, v118, s[0:1]
	v_cndmask_b32_e32 v118, 0, v232, vcc
	v_sub_f32_e32 v99, v99, v118
